# in-loop plain epilogue: LDS wait that served the (now hoisted) row-scale reads removed, so the epilogue VALU no longer waits for the fragment reads of its segment
# baseline (speedup 1.0000x reference)
; #define PG8_STAGE(bufoff, gbase, voff) do { _Pragma("unroll") for (int _i = 0; _i < 2; ++_i) \
;         __builtin_amdgcn_global_load_lds((const unsigned*)((const char*)(gbase) + (voff)[_i]), (LAS unsigned*)(lds + (bufoff) + ldsw + _i * 8192), 16, 0, 0); } while (0)
; #define PG8_LDA(dst, b, h) do { _Pragma("unroll") for (int m = 0; m < 4; ++m) _Pragma("unroll") for (int k = 0; k < 2; ++k) dst[m][k] = *(const LAS bf16x8*)(lds + PG8_SA(b, h) + aoff + m * 2048 + k * 1024); } while (0)
; #define PG8_LDB(dst, b, h) do { _Pragma("unroll") for (int n = 0; n < 2; ++n) _Pragma("unroll") for (int k = 0; k < 2; ++k) dst[n][k] = *(const LAS bf16x8*)(lds + PG8_SB(b, h) + boff + n * 2048 + k * 1024); } while (0)
; #define PG8_MMA(ai, bj, At, Bt) do { __builtin_amdgcn_s_setprio(1); _Pragma("unroll") for (int m = 0; m < 4; ++m) _Pragma("unroll") for (int n = 0; n < 2; ++n) _Pragma("unroll") for (int k = 0; k < 2; ++k) \
;         acc[ai][bj][m][n] = __builtin_amdgcn_mfma_f32_16x16x32_bf16(Bt[n][k], At[m][k], acc[ai][bj][m][n], 0, 0, 0); __builtin_amdgcn_s_setprio(0); } while (0)
; #define PG8_WAIT_L(n) asm volatile("s_waitcnt lgkmcnt(" #n ")" ::: "memory")
; #define PG8_BAR __builtin_amdgcn_s_barrier()
; #define PG8_SCHED __builtin_amdgcn_sched_barrier(0)
; template <class Epi>
; __device__ __forceinline__ void gemm_phase(LAS unsigned char* lds, const Gemm g, const StaticOrder& S, const Epi& E) {
;     ...
;             PG8_WAIT_L(8); PG8_BAR; PG8_WAIT_L(0); PG8_MMA(0, 0, At, B0); PG8_BAR; PG8_SCHED;
;             PG8_LDB(B1, 1, 1); PG8_STAGE(PG8_SB(1, 0), b3, voffB);
;             PG8_BAR; PG8_WAIT_L(0); PG8_MMA(0, 1, At, B1); PG8_BAR;
;             PG8_LDA(At, 1, 1); PG8_STAGE(PG8_SA(1, 0), a3, voffA);
;             PG8_BAR; PG8_WAIT_L(0); PG8_MMA(1, 0, At, B0); PG8_BAR; PG8_SCHED;
;             PG8_STAGE(PG8_SB(1, 1), b3 + hstepB, voffB);
.Lrs_skip:
	s_waitcnt vmcnt(8) lgkmcnt(0)
	s_barrier
	v_mfma_f32_16x16x32_bf16 v[124:127], v[130:133], v[146:149], v[124:127]
	v_mfma_f32_16x16x32_bf16 v[120:123], v[138:141], v[146:149], v[120:123]
	v_mfma_f32_16x16x32_bf16 v[112:115], v[130:133], v[154:157], v[112:115]
	v_mfma_f32_16x16x32_bf16 v[104:107], v[138:141], v[154:157], v[104:107]
	v_mfma_f32_16x16x32_bf16 v[96:99], v[130:133], v[162:165], v[96:99]
	v_mfma_f32_16x16x32_bf16 v[88:91], v[138:141], v[162:165], v[88:91]
	v_mfma_f32_16x16x32_bf16 v[80:83], v[130:133], v[194:197], v[80:83]
	v_mfma_f32_16x16x32_bf16 v[72:75], v[138:141], v[194:197], v[72:75]
	v_mfma_f32_16x16x32_bf16 v[124:127], v[134:137], v[150:153], v[124:127]
	v_mfma_f32_16x16x32_bf16 v[120:123], v[142:145], v[150:153], v[120:123]
	v_mfma_f32_16x16x32_bf16 v[112:115], v[134:137], v[158:161], v[112:115]
	v_mfma_f32_16x16x32_bf16 v[104:107], v[142:145], v[158:161], v[104:107]
	v_mfma_f32_16x16x32_bf16 v[96:99], v[134:137], v[190:193], v[96:99]
	v_mfma_f32_16x16x32_bf16 v[88:91], v[142:145], v[190:193], v[88:91]
	v_mfma_f32_16x16x32_bf16 v[80:83], v[134:137], v[198:201], v[80:83]
	v_mfma_f32_16x16x32_bf16 v[72:75], v[142:145], v[198:201], v[72:75]
	v_mfma_f32_16x16x32_bf16 v[116:119], v[202:205], v[146:149], v[116:119]
	v_mfma_f32_16x16x32_bf16 v[108:111], v[234:237], v[146:149], v[108:111]
	v_mfma_f32_16x16x32_bf16 v[100:103], v[202:205], v[154:157], v[100:103]
	v_mfma_f32_16x16x32_bf16 v[92:95], v[234:237], v[154:157], v[92:95]
	v_mfma_f32_16x16x32_bf16 v[84:87], v[202:205], v[162:165], v[84:87]
	v_mfma_f32_16x16x32_bf16 v[76:79], v[234:237], v[162:165], v[76:79]
	v_mfma_f32_16x16x32_bf16 v[68:71], v[202:205], v[194:197], v[68:71]
	v_mfma_f32_16x16x32_bf16 v[64:67], v[234:237], v[194:197], v[64:67]
	v_mfma_f32_16x16x32_bf16 v[116:119], v[230:233], v[150:153], v[116:119]
	v_mfma_f32_16x16x32_bf16 v[108:111], v[238:241], v[150:153], v[108:111]
	v_mfma_f32_16x16x32_bf16 v[100:103], v[230:233], v[158:161], v[100:103]
	v_mfma_f32_16x16x32_bf16 v[92:95], v[238:241], v[158:161], v[92:95]
	v_mfma_f32_16x16x32_bf16 v[84:87], v[230:233], v[190:193], v[84:87]
	v_mfma_f32_16x16x32_bf16 v[76:79], v[238:241], v[190:193], v[76:79]
	v_mfma_f32_16x16x32_bf16 v[68:71], v[230:233], v[198:201], v[68:71]
	v_mfma_f32_16x16x32_bf16 v[64:67], v[238:241], v[198:201], v[64:67]
	s_barrier
	ds_read_b128 v[146:149], v228 offset:49152
	ds_read_b128 v[150:153], v228 offset:50176
	ds_read_b128 v[154:157], v228 offset:51200
	ds_read_b128 v[158:161], v228 offset:52224
	ds_read_b128 v[162:165], v228 offset:53248
	ds_read_b128 v[190:193], v228 offset:54272
	ds_read_b128 v[194:197], v228 offset:55296
	ds_read_b128 v[198:201], v228 offset:56320
	s_add_i32 s44, s57, 0x18000
	v_lshl_add_u64 v[166:167], v[166:167], 0, s[88:89]
	s_mov_b32 m0, s44
	v_lshl_add_u64 v[206:207], v[206:207], 0, s[88:89]
	global_load_lds_dwordx4 v[166:167], off
	s_add_i32 m0, s44, 0x2000
	v_lshl_add_u64 v[242:243], v[242:243], 0, s[88:89]
	global_load_lds_dwordx4 v[206:207], off
	s_mov_b32 m0, s60
	v_lshl_add_u64 v[244:245], v[244:245], 0, s[88:89]
	global_load_lds_dwordx4 v[242:243], off
	s_mov_b32 m0, s61
	s_add_i32 s44, s57, 0x1c000
	v_lshl_add_u64 v[246:247], v[246:247], 0, s[88:89]
	global_load_lds_dwordx4 v[244:245], off
	s_mov_b32 m0, s44
	v_lshl_add_u64 v[248:249], v[248:249], 0, s[88:89]
	global_load_lds_dwordx4 v[246:247], off
	s_add_i32 m0, s44, 0x2000
	s_nop 0
	global_load_lds_dwordx4 v[248:249], off
	s_cmp_lt_u32 s35, s16
	s_cbranch_scc1 .Le0_skip
	s_cmp_eq_u32 s32, 0
	s_cbranch_scc1 .Le0_skip
;     __device__ __forceinline__ void operator()(const f32x4 (&acc)[2][2][4][2], const Unit& u, int wr, int wc, int fr, int fq, const LAS float* rsl) const {
;     ...
;                 const float rstd = rsqrtf(rs[ai][m] * (1.f / 1024.f) + EPS);
;                 bf16_t* rp = proj + (size_t)row * PW + wc * 32 + 8 * fq;
;                 if (pn < 9) {
; #pragma unroll
;                     for (int bj = 0; bj < 2; ++bj) store8bf_nt(rp + pn * 256 + bj * 128, acc[ai][bj][m][0] * rstd, acc[ai][bj][m][1] * rstd);
	v_add_u32_e32 v242, s34, v171
	v_mad_i64_i32 v[244:245], s[44:45], v242, s0, v[182:183]
	s_lshl_b32 s46, s48, 9
	s_mov_b32 s47, 0
	v_lshl_add_u64 v[244:245], v[244:245], 0, s[46:47]
	v_pk_mul_f32 v[124:125], v[124:125], v[250:251] op_sel_hi:[1,0]
	v_pk_mul_f32 v[126:127], v[126:127], v[250:251] op_sel_hi:[1,0]
	v_pk_mul_f32 v[120:121], v[120:121], v[250:251] op_sel_hi:[1,0]
	v_pk_mul_f32 v[122:123], v[122:123], v[250:251] op_sel_hi:[1,0]
	v_cvt_pk_bf16_f32 v124, v124, v125
	v_cvt_pk_bf16_f32 v125, v126, v127
	v_cvt_pk_bf16_f32 v126, v120, v121
	v_cvt_pk_bf16_f32 v127, v122, v123
	global_store_dwordx4 v[244:245], v[124:127], off nt
	v_pk_mul_f32 v[116:117], v[116:117], v[250:251] op_sel_hi:[1,0]
	v_pk_mul_f32 v[118:119], v[118:119], v[250:251] op_sel_hi:[1,0]
	v_pk_mul_f32 v[108:109], v[108:109], v[250:251] op_sel_hi:[1,0]
	v_pk_mul_f32 v[110:111], v[110:111], v[250:251] op_sel_hi:[1,0]
	v_cvt_pk_bf16_f32 v116, v116, v117
	v_cvt_pk_bf16_f32 v117, v118, v119
	v_cvt_pk_bf16_f32 v118, v108, v109
	v_cvt_pk_bf16_f32 v119, v110, v111
	global_store_dwordx4 v[244:245], v[116:119], off offset:256 nt
	v_add_co_u32_e32 v244, vcc, 0x22000, v244
	s_nop 1
	v_addc_co_u32_e32 v245, vcc, 0, v245, vcc
	v_pk_mul_f32 v[112:113], v[112:113], v[250:251] op_sel:[0,1] op_sel_hi:[1,1]
	v_pk_mul_f32 v[114:115], v[114:115], v[250:251] op_sel:[0,1] op_sel_hi:[1,1]
	v_pk_mul_f32 v[104:105], v[104:105], v[250:251] op_sel:[0,1] op_sel_hi:[1,1]
	v_pk_mul_f32 v[106:107], v[106:107], v[250:251] op_sel:[0,1] op_sel_hi:[1,1]
	v_cvt_pk_bf16_f32 v112, v112, v113
	v_cvt_pk_bf16_f32 v113, v114, v115
	v_cvt_pk_bf16_f32 v114, v104, v105
	v_cvt_pk_bf16_f32 v115, v106, v107
	global_store_dwordx4 v[244:245], v[112:115], off nt
	v_pk_mul_f32 v[100:101], v[100:101], v[250:251] op_sel:[0,1] op_sel_hi:[1,1]
	v_pk_mul_f32 v[102:103], v[102:103], v[250:251] op_sel:[0,1] op_sel_hi:[1,1]
	v_pk_mul_f32 v[92:93], v[92:93], v[250:251] op_sel:[0,1] op_sel_hi:[1,1]
	v_pk_mul_f32 v[94:95], v[94:95], v[250:251] op_sel:[0,1] op_sel_hi:[1,1]
	v_cvt_pk_bf16_f32 v100, v100, v101
	v_cvt_pk_bf16_f32 v101, v102, v103
	v_cvt_pk_bf16_f32 v102, v92, v93
	v_cvt_pk_bf16_f32 v103, v94, v95
	global_store_dwordx4 v[244:245], v[100:103], off offset:256 nt
	v_add_co_u32_e32 v244, vcc, 0x22000, v244
	s_nop 1
	v_addc_co_u32_e32 v245, vcc, 0, v245, vcc
	v_pk_mul_f32 v[96:97], v[96:97], v[252:253] op_sel_hi:[1,0]
	v_pk_mul_f32 v[98:99], v[98:99], v[252:253] op_sel_hi:[1,0]
	v_pk_mul_f32 v[88:89], v[88:89], v[252:253] op_sel_hi:[1,0]
	v_pk_mul_f32 v[90:91], v[90:91], v[252:253] op_sel_hi:[1,0]
	v_cvt_pk_bf16_f32 v96, v96, v97
	v_cvt_pk_bf16_f32 v97, v98, v99
	v_cvt_pk_bf16_f32 v98, v88, v89
	v_cvt_pk_bf16_f32 v99, v90, v91
	global_store_dwordx4 v[244:245], v[96:99], off nt
	v_pk_mul_f32 v[84:85], v[84:85], v[252:253] op_sel_hi:[1,0]
	v_pk_mul_f32 v[86:87], v[86:87], v[252:253] op_sel_hi:[1,0]
	v_pk_mul_f32 v[76:77], v[76:77], v[252:253] op_sel_hi:[1,0]
	v_pk_mul_f32 v[78:79], v[78:79], v[252:253] op_sel_hi:[1,0]
	v_cvt_pk_bf16_f32 v84, v84, v85
	v_cvt_pk_bf16_f32 v85, v86, v87
	v_cvt_pk_bf16_f32 v86, v76, v77
	v_cvt_pk_bf16_f32 v87, v78, v79
	global_store_dwordx4 v[244:245], v[84:87], off offset:256 nt
	v_add_co_u32_e32 v244, vcc, 0x22000, v244
	s_nop 1
	v_addc_co_u32_e32 v245, vcc, 0, v245, vcc
	v_pk_mul_f32 v[80:81], v[80:81], v[252:253] op_sel:[0,1] op_sel_hi:[1,1]
	v_pk_mul_f32 v[82:83], v[82:83], v[252:253] op_sel:[0,1] op_sel_hi:[1,1]
	v_pk_mul_f32 v[72:73], v[72:73], v[252:253] op_sel:[0,1] op_sel_hi:[1,1]
	v_pk_mul_f32 v[74:75], v[74:75], v[252:253] op_sel:[0,1] op_sel_hi:[1,1]
	v_cvt_pk_bf16_f32 v80, v80, v81
	v_cvt_pk_bf16_f32 v81, v82, v83
	v_cvt_pk_bf16_f32 v82, v72, v73
	v_cvt_pk_bf16_f32 v83, v74, v75
	global_store_dwordx4 v[244:245], v[80:83], off nt
	v_pk_mul_f32 v[68:69], v[68:69], v[252:253] op_sel:[0,1] op_sel_hi:[1,1]
	v_pk_mul_f32 v[70:71], v[70:71], v[252:253] op_sel:[0,1] op_sel_hi:[1,1]
	v_pk_mul_f32 v[64:65], v[64:65], v[252:253] op_sel:[0,1] op_sel_hi:[1,1]
	v_pk_mul_f32 v[66:67], v[66:67], v[252:253] op_sel:[0,1] op_sel_hi:[1,1]
	v_cvt_pk_bf16_f32 v68, v68, v69
	v_cvt_pk_bf16_f32 v69, v70, v71
	v_cvt_pk_bf16_f32 v70, v64, v65
	v_cvt_pk_bf16_f32 v71, v66, v67
	global_store_dwordx4 v[244:245], v[68:71], off offset:256 nt
	s_waitcnt vmcnt(16) lgkmcnt(0)
	s_barrier
	s_branch .Le0_join
